# dense attention: max-free main loop when Cauchy-Schwarz bound on normed q.k scores (from q/k norm gains) proves exp2 safe; general loop kept as fallback
# speedup vs baseline: 1.0395x; 1.0346x over previous
.LBB0_384:
	v_readlane_b32 s98, v251, 36
	v_readlane_b32 s99, v251, 37
	v_readlane_b32 s100, v251, 4
	v_readlane_b32 s101, v251, 5
	v_readlane_b32 s10, v254, 6
	s_lshl_b32 s10, s10, 8
	s_add_u32 s98, s98, s10
	s_addc_u32 s99, s99, 0
	s_add_u32 s100, s100, s10
	s_addc_u32 s101, s101, 0
	v_lshlrev_b32_e32 v0, 2, v207
	global_load_dword v1, v0, s[98:99]
	global_load_dword v2, v0, s[100:101]
	s_waitcnt vmcnt(0)
	v_and_b32_e32 v1, 0x7fffffff, v1
	v_and_b32_e32 v2, 0x7fffffff, v2
	s_mov_b32 s98, 0
	s_mov_b32 s99, 0
	s_mov_b32 s100, 0
.Lattn_guard_loop:
	v_readlane_b32 s101, v1, s98
	s_max_u32 s99, s99, s101
	v_readlane_b32 s101, v2, s98
	s_max_u32 s100, s100, s101
	s_add_i32 s98, s98, 1
	s_cmp_lt_u32 s98, 64
	s_cbranch_scc1 .Lattn_guard_loop
	v_mov_b32_e32 v0, s99
	v_mul_f32_e32 v0, s100, v0
	s_nop 0
	v_readfirstlane_b32 s98, v0
	s_cmp_le_u32 s98, 0x40800000
	s_cselect_b32 s101, 1, 0
	s_mov_b32 s28, 0
	v_readlane_b32 s6, v253, 1
	v_readlane_b32 s7, v253, 5
	v_readlane_b32 s16, v253, 6
	v_readlane_b32 s17, v253, 7
	v_readlane_b32 s25, v253, 8
	v_readlane_b32 s26, v253, 9
	v_readlane_b32 s27, v253, 10
	v_readlane_b32 s45, v253, 11
	s_branch .LBB0_386

.LBB0_386:
	v_mov_b32_e32 v84, v206
	s_add_i32 s10, s28, s6
	s_lshl_b32 s10, s10, 8
	v_readfirstlane_b32 s35, v84
	s_ashr_i32 s34, s35, 6
	v_readlane_b32 s8, v253, 3
	v_readlane_b32 s9, v253, 4
	s_add_u32 s10, s8, s10
	s_addc_u32 s11, s9, 0
	s_lshl_b32 s12, s34, 5
	s_ashr_i32 s13, s12, 31
	s_add_u32 s10, s10, s12
	s_addc_u32 s11, s11, s13
	s_mul_i32 s12, s11, 0xa00
	s_mul_hi_u32 s13, s10, 0xa00
	s_add_i32 s13, s13, s12
	s_mul_i32 s12, s10, 0xa00
	s_lshl_b64 s[12:13], s[12:13], 1
	s_add_u32 s40, s7, s12
	s_addc_u32 s41, s16, s13
	s_lshl_b32 s20, s34, 9
	s_ashr_i32 s21, s20, 31
	s_and_b32 s36, s35, 0x3fffffc0
	s_lshl_b64 s[20:21], s[20:21], 1
	v_and_b32_e32 v222, 63, v84
	s_add_u32 s30, s17, s20
	s_addc_u32 s31, s25, s21
	v_lshlrev_b32_e32 v188, 4, v222
	v_lshl_add_u64 v[204:205], s[30:31], 0, v[188:189]
	s_lshl_b32 s30, s35, 3
	s_and_b32 s30, s30, 0xfffff800
	s_ashr_i32 s31, s30, 31
	s_lshl_b64 s[30:31], s[30:31], 1
	s_add_u32 s38, s26, s30
	s_addc_u32 s39, s27, s31
	s_lshl_b32 s35, s34, 4
	v_bfe_u32 v85, v84, 2, 4
	v_and_or_b32 v0, s35, 48, v85
	v_lshlrev_b32_e32 v0, 6, v0
	s_waitcnt lgkmcnt(0)
	v_mov_b32_e32 v1, v189
	v_lshl_add_u64 v[0:1], s[38:39], 0, v[0:1]
	s_lshl_b32 s38, s34, 10
	v_lshlrev_b32_e32 v223, 3, v84
	s_cmp_lg_u32 0, -1
	v_and_b32_e32 v217, 24, v223
	s_cselect_b32 s35, 0, 0
	v_lshlrev_b32_e32 v2, 1, v217
	v_mov_b32_e32 v3, v189
	s_add_i32 s39, s38, s35
	s_mov_b32 s37, m0
	s_mov_b32 m0, s39
	s_nop 0
	global_load_lds_dwordx4 v[204:205], off
	s_mov_b32 m0, s37
	s_mov_b64 s[8:9], 0x2000
	v_and_b32_e32 v215, 31, v84
	v_bfe_u32 v216, v84, 5, 1
	v_lshl_add_u64 v[202:203], v[0:1], 0, v[2:3]
	s_add_i32 s35, s39, 0x6000
	s_mov_b32 s37, m0
	s_mov_b32 m0, s35
	s_nop 0
	global_load_lds_dwordx4 v[202:203], off
	s_mov_b32 m0, s37
	v_lshl_add_u64 v[0:1], v[204:205], 0, s[8:9]
	s_add_i32 s37, s39, 0x2000
	s_mov_b32 s42, m0
	s_mov_b32 m0, s37
	s_nop 0
	global_load_lds_dwordx4 v[0:1], off
	s_mov_b32 m0, s42
	v_mul_u32_u24_e32 v0, 0xa00, v215
	v_lshlrev_b32_e32 v226, 4, v216
	v_lshl_or_b32 v8, v0, 1, v226
	global_load_dwordx4 v[156:159], v8, s[40:41]
	global_load_dwordx4 v[152:155], v8, s[40:41] offset:32
	global_load_dwordx4 v[140:143], v8, s[40:41] offset:64
	global_load_dwordx4 v[132:135], v8, s[40:41] offset:96
	v_mov_b32_e32 v0, v189
	v_mov_b32_e32 v1, v189
	v_mov_b32_e32 v2, v189
	v_mov_b32_e32 v4, v189
	v_mov_b32_e32 v5, v189
	v_mov_b32_e32 v6, v189
	v_mov_b32_e32 v7, v189
	v_mov_b32_e32 v8, v189
	v_mov_b32_e32 v9, v189
	v_mov_b32_e32 v10, v189
	v_mov_b32_e32 v11, v189
	v_mov_b32_e32 v12, v189
	v_mov_b32_e32 v13, v189
	v_mov_b32_e32 v14, v189
	v_mov_b32_e32 v15, v189
	v_lshlrev_b32_e32 v16, 10, v216
	v_lshlrev_b32_e32 v17, 4, v215
	s_mov_b64 s[40:41], 0x4000
	v_add3_u32 v225, 0, v16, v17
	v_lshl_add_u64 v[16:17], v[204:205], 0, s[40:41]
	s_add_i32 s37, s39, 0x4000
	s_mov_b32 s40, m0
	s_mov_b32 m0, s37
	s_nop 0
	global_load_lds_dwordx4 v[16:17], off
	s_mov_b32 m0, s40
	s_waitcnt vmcnt(3) lgkmcnt(0)
	s_barrier
	ds_read_b128 v[32:35], v225
	ds_read_b128 v[36:39], v225 offset:512
	s_lshl_b32 s36, s36, 2
	s_add_i32 s40, s36, 0
	s_mov_b64 s[36:37], 0x6000
	v_mov_b32_e32 v184, 0
	s_mov_b32 s41, -1
	s_movk_i32 s43, 0x2000
	s_movk_i32 s42, 0x4000
	s_mov_b64 s[48:49], 0x2000
	v_lshl_add_u32 v220, v215, 2, s40
	s_waitcnt vmcnt(0) lgkmcnt(0)
	v_mfma_f32_32x32x16_bf16 v[16:31], v[32:35], v[156:159], v[0:15]
	v_mfma_f32_32x32x16_bf16 v[0:15], v[36:39], v[156:159], v[0:15]
	ds_read_b128 v[32:35], v225 offset:2048
	ds_read_b128 v[36:39], v225 offset:2560
	s_waitcnt lgkmcnt(1)
	v_mfma_f32_32x32x16_bf16 v[16:31], v[32:35], v[152:155], v[16:31]
	s_waitcnt lgkmcnt(0)
	v_mfma_f32_32x32x16_bf16 v[0:15], v[36:39], v[152:155], v[0:15]
	ds_read_b128 v[32:35], v225 offset:4096
	ds_read_b128 v[36:39], v225 offset:4608
	s_waitcnt lgkmcnt(1)
	v_mfma_f32_32x32x16_bf16 v[16:31], v[32:35], v[140:143], v[16:31]
	ds_read_b128 v[32:35], v225 offset:6144
	s_waitcnt lgkmcnt(1)
	v_mfma_f32_32x32x16_bf16 v[0:15], v[36:39], v[140:143], v[0:15]
	ds_read_b128 v[36:39], v225 offset:6656
	s_waitcnt lgkmcnt(1)
	v_mfma_f32_32x32x16_bf16 v[16:31], v[32:35], v[132:135], v[16:31]
	v_lshlrev_b32_e32 v32, 1, v84
	v_lshlrev_b32_e32 v33, 4, v84
	v_and_b32_e32 v218, 32, v32
	v_and_b32_e32 v32, 0xc0, v33
	v_lshl_or_b32 v219, v216, 8, v32
	v_add_u32_e32 v80, 0, v218
	v_add3_u32 v224, v80, v217, v219
	s_waitcnt lgkmcnt(0)
	v_mfma_f32_32x32x16_bf16 v[0:15], v[36:39], v[132:135], v[0:15]
	s_nop 15
	s_nop 7
	s_nop 0
	v_max3_f32 v32, v16, v17, v0
	v_max3_f32 v33, v18, v19, v1
	s_nop 0
	v_max3_f32 v32, v32, v2, v3
	v_max3_f32 v33, v33, v22, v23
	s_nop 0
	v_max3_f32 v32, v32, v20, v21
	v_max3_f32 v33, v33, v6, v7
	s_nop 0
	v_max3_f32 v32, v32, v4, v5
	v_max3_f32 v33, v33, v26, v27
	s_nop 0
	v_max3_f32 v32, v32, v24, v25
	v_max3_f32 v33, v33, v10, v11
	s_nop 0
	v_max3_f32 v32, v32, v8, v9
	v_max3_f32 v33, v33, v30, v31
	s_nop 0
	v_max3_f32 v32, v32, v28, v29
	v_max3_f32 v33, v33, v14, v15
	s_nop 0
	v_max3_f32 v32, v32, v12, v13
	s_nop 0
	v_max_f32_e32 v32, v32, v33
	s_nop 0
	v_mov_b32_e32 v33, v32
	s_nop 1
	v_permlane32_swap_b32_e32 v32, v33
	v_max_f32_e32 v32, v32, v33
	s_nop 0
	v_add_f32_e32 v221, v189, v32
	v_sub_f32_e32 v16, v16, v32
	v_sub_f32_e32 v0, v0, v32
	v_sub_f32_e32 v17, v17, v32
	v_sub_f32_e32 v1, v1, v32
	v_sub_f32_e32 v18, v18, v32
	v_sub_f32_e32 v2, v2, v32
	v_sub_f32_e32 v19, v19, v32
	v_sub_f32_e32 v3, v3, v32
	v_sub_f32_e32 v20, v20, v32
	v_sub_f32_e32 v4, v4, v32
	v_sub_f32_e32 v21, v21, v32
	v_sub_f32_e32 v5, v5, v32
	v_sub_f32_e32 v22, v22, v32
	v_sub_f32_e32 v6, v6, v32
	v_sub_f32_e32 v23, v23, v32
	v_sub_f32_e32 v7, v7, v32
	v_sub_f32_e32 v24, v24, v32
	v_sub_f32_e32 v8, v8, v32
	v_sub_f32_e32 v25, v25, v32
	v_sub_f32_e32 v9, v9, v32
	v_sub_f32_e32 v26, v26, v32
	v_sub_f32_e32 v10, v10, v32
	v_sub_f32_e32 v27, v27, v32
	v_sub_f32_e32 v11, v11, v32
	v_sub_f32_e32 v28, v28, v32
	v_sub_f32_e32 v12, v12, v32
	v_sub_f32_e32 v29, v29, v32
	v_sub_f32_e32 v13, v13, v32
	v_sub_f32_e32 v30, v30, v32
	v_sub_f32_e32 v14, v14, v32
	v_sub_f32_e32 v31, v31, v32
	v_sub_f32_e32 v15, v15, v32
	s_nop 0
	v_xor_b32_e32 v32, 0x80000000, v221
	v_mov_b32_e32 v33, v32
	v_mov_b32_e32 v34, v32
	v_mov_b32_e32 v35, v32
	v_mov_b32_e32 v36, v32
	v_mov_b32_e32 v37, v32
	v_mov_b32_e32 v38, v32
	v_mov_b32_e32 v39, v32
	v_mov_b32_e32 v40, v32
	v_mov_b32_e32 v41, v32
	v_mov_b32_e32 v42, v32
	v_mov_b32_e32 v43, v32
	v_mov_b32_e32 v44, v32
	v_mov_b32_e32 v45, v32
	v_mov_b32_e32 v46, v32
	v_mov_b32_e32 v47, v32
	s_waitcnt vmcnt(0) lgkmcnt(0)
	s_barrier
	v_exp_f32_e32 v48, v0
	v_exp_f32_e32 v49, v1
	v_lshl_add_u64 v[0:1], v[204:205], 0, s[36:37]
	s_mov_b32 s36, m0
	s_mov_b32 m0, s39
	s_nop 0
	global_load_lds_dwordx4 v[0:1], off
	s_mov_b32 m0, s36
	v_lshl_add_u64 v[0:1], v[202:203], 0, s[8:9]
	s_add_i32 s36, s39, 0x8000
	s_mov_b32 s37, m0
	s_mov_b32 m0, s36
	s_nop 0
	global_load_lds_dwordx4 v[0:1], off
	s_mov_b32 m0, s37
	ds_read_b128 v[80:83], v225 offset:8192
	ds_read_b128 v[164:167], v225 offset:8704
	ds_read_b128 v[168:171], v225 offset:10240
	ds_read_b128 v[160:163], v225 offset:10752
	ds_read_b128 v[124:127], v225 offset:12288
	ds_read_b128 v[120:123], v225 offset:12800
	ds_read_b128 v[116:119], v225 offset:14336
	ds_read_b128 v[112:115], v225 offset:14848
	v_readlane_b32 s8, v253, 53
	s_add_u32 s20, s8, s20
	v_readlane_b32 s8, v253, 54
	s_addc_u32 s21, s8, s21
	v_exp_f32_e32 v64, v16
	v_exp_f32_e32 v65, v17
	v_exp_f32_e32 v66, v18
	v_exp_f32_e32 v67, v19
	v_exp_f32_e32 v68, v20
	v_exp_f32_e32 v69, v21
	v_exp_f32_e32 v70, v22
	v_exp_f32_e32 v71, v23
	v_exp_f32_e32 v72, v24
	v_exp_f32_e32 v73, v25
	v_exp_f32_e32 v74, v26
	v_exp_f32_e32 v75, v27
	v_exp_f32_e32 v76, v28
	v_exp_f32_e32 v77, v29
	v_exp_f32_e32 v78, v30
	v_exp_f32_e32 v79, v31
	v_exp_f32_e32 v50, v2
	v_exp_f32_e32 v51, v3
	v_exp_f32_e32 v52, v4
	v_exp_f32_e32 v53, v5
	v_exp_f32_e32 v54, v6
	v_exp_f32_e32 v55, v7
	v_exp_f32_e32 v56, v8
	v_exp_f32_e32 v57, v9
	v_exp_f32_e32 v58, v10
	v_exp_f32_e32 v59, v11
	v_exp_f32_e32 v60, v12
	v_exp_f32_e32 v61, v13
	v_exp_f32_e32 v62, v14
	v_exp_f32_e32 v63, v15
	v_lshl_add_u64 v[180:181], s[20:21], 0, v[188:189]
	v_and_b32_e32 v0, 3, v84
	s_and_b32 s20, s38, 0xc00
	s_waitcnt vmcnt(2) lgkmcnt(0)
	s_barrier
	v_lshlrev_b32_e32 v0, 4, v0
	v_lshl_or_b32 v1, v85, 6, s20
	v_readlane_b32 s8, v253, 55
	v_or3_b32 v0, s30, v0, v1
	v_mov_b32_e32 v1, s31
	v_readlane_b32 s9, v253, 56
	v_cmp_gt_u32_e64 s[36:37], 32, v222
	s_mov_b32 s20, 0
	v_lshl_add_u64 v[182:183], s[8:9], 0, v[0:1]
	s_movk_i32 s9, 0x60
	v_mov_b32_e32 v0, 0
	v_mov_b32_e32 v1, v184
	v_mov_b32_e32 v2, v184
	v_mov_b32_e32 v3, v184
	v_mov_b32_e32 v4, v184
	v_mov_b32_e32 v5, v184
	v_mov_b32_e32 v6, v184
	v_mov_b32_e32 v7, v184
	v_mov_b32_e32 v8, v184
	v_mov_b32_e32 v9, v184
	v_mov_b32_e32 v10, v184
	v_mov_b32_e32 v11, v184
	v_mov_b32_e32 v12, v184
	v_mov_b32_e32 v13, v184
	v_mov_b32_e32 v14, v184
	v_mov_b32_e32 v15, v184
	v_mov_b32_e32 v16, 0
	v_mov_b32_e32 v17, v184
	v_mov_b32_e32 v18, v184
	v_mov_b32_e32 v19, v184
	v_mov_b32_e32 v20, v184
	v_mov_b32_e32 v21, v184
	v_mov_b32_e32 v22, v184
	v_mov_b32_e32 v23, v184
	v_mov_b32_e32 v24, v184
	v_mov_b32_e32 v25, v184
	v_mov_b32_e32 v26, v184
	v_mov_b32_e32 v27, v184
	v_mov_b32_e32 v28, v184
	v_mov_b32_e32 v29, v184
	v_mov_b32_e32 v30, v184
	v_mov_b32_e32 v31, v184
	s_cmp_lg_u32 s101, 0
	s_cbranch_scc1 .Lattn_fast_top

.Lattn_fast_top:
	v_add_u32_e32 v185, s20, v224
	ds_read_b64_tr_b16 v[176:177], v185 offset:24576
	ds_read_b64_tr_b16 v[178:179], v185 offset:25088
	s_waitcnt lgkmcnt(9)
	v_mfma_f32_32x32x16_bf16 v[96:111], v[80:83], v[156:159], v[32:47]
	v_add_f32_e32 v84, v64, v65
	v_add_f32_e32 v84, v66, v84
	v_add_f32_e32 v84, v67, v84
	v_add_f32_e32 v84, v68, v84
	v_add_f32_e32 v84, v69, v84
	v_cvt_pk_bf16_f32 v148, v64, v65
	v_cvt_pk_bf16_f32 v149, v66, v67
	ds_read_b64_tr_b16 v[172:173], v185 offset:28672
	ds_read_b64_tr_b16 v[174:175], v185 offset:29184
	v_add_f32_e32 v64, v70, v84
	s_waitcnt lgkmcnt(10)
	v_mfma_f32_32x32x16_bf16 v[80:95], v[164:167], v[156:159], v[32:47]
	v_add_f32_e32 v64, v71, v64
	v_add_f32_e32 v64, v72, v64
	v_add_f32_e32 v128, v73, v64
	v_cvt_pk_bf16_f32 v150, v68, v69
	v_cvt_pk_bf16_f32 v151, v70, v71
	ds_read_b64_tr_b16 v[64:65], v185 offset:25600
	ds_read_b64_tr_b16 v[66:67], v185 offset:26112
	s_waitcnt lgkmcnt(11)
	v_mfma_f32_32x32x16_bf16 v[96:111], v[168:171], v[152:155], v[96:111]
	v_add_f32_e32 v68, v74, v128
	v_add_f32_e32 v68, v75, v68
	v_add_f32_e32 v68, v76, v68
	v_add_f32_e32 v128, v77, v68
	v_cvt_pk_bf16_f32 v144, v72, v73
	v_cvt_pk_bf16_f32 v145, v74, v75
	ds_read_b64_tr_b16 v[68:69], v185 offset:29696
	ds_read_b64_tr_b16 v[70:71], v185 offset:30208
	s_waitcnt lgkmcnt(12)
	v_mfma_f32_32x32x16_bf16 v[80:95], v[160:163], v[152:155], v[80:95]
	v_add_f32_e32 v72, v78, v128
	v_add_f32_e32 v72, v79, v72
	v_add_f32_e32 v72, v48, v72
	v_add_f32_e32 v128, v49, v72
	v_cvt_pk_bf16_f32 v146, v76, v77
	v_cvt_pk_bf16_f32 v147, v78, v79
	ds_read_b64_tr_b16 v[72:73], v185 offset:26624
	ds_read_b64_tr_b16 v[74:75], v185 offset:27136
	s_waitcnt lgkmcnt(13)
	v_mfma_f32_32x32x16_bf16 v[96:111], v[124:127], v[140:143], v[96:111]
	v_add_f32_e32 v76, v50, v128
	v_add_f32_e32 v76, v51, v76
	v_add_f32_e32 v76, v52, v76
	v_add_f32_e32 v76, v53, v76
	v_cvt_pk_bf16_f32 v136, v48, v49
	v_cvt_pk_bf16_f32 v137, v50, v51
	ds_read_b64_tr_b16 v[48:49], v185 offset:30720
	ds_read_b64_tr_b16 v[50:51], v185 offset:31232
	s_waitcnt lgkmcnt(14)
	v_mfma_f32_32x32x16_bf16 v[80:95], v[120:123], v[140:143], v[80:95]
	v_add_f32_e32 v76, v54, v76
	v_add_f32_e32 v76, v55, v76
	v_add_f32_e32 v76, v56, v76
	v_add_f32_e32 v76, v57, v76
	v_cvt_pk_bf16_f32 v138, v52, v53
	v_cvt_pk_bf16_f32 v139, v54, v55
	ds_read_b64_tr_b16 v[52:53], v185 offset:27648
	ds_read_b64_tr_b16 v[54:55], v185 offset:28160
	s_waitcnt lgkmcnt(14)
	v_mfma_f32_32x32x16_bf16 v[96:111], v[116:119], v[132:135], v[96:111]
	v_add_f32_e32 v76, v58, v76
	v_add_f32_e32 v76, v59, v76
	v_add_f32_e32 v76, v60, v76
	v_add_f32_e32 v76, v61, v76
	v_cvt_pk_bf16_f32 v128, v56, v57
	v_cvt_pk_bf16_f32 v129, v58, v59
	ds_read_b64_tr_b16 v[56:57], v185 offset:31744
	ds_read_b64_tr_b16 v[58:59], v185 offset:32256
	v_mfma_f32_32x32x16_bf16 v[80:95], v[112:115], v[132:135], v[80:95]
	v_add_f32_e32 v76, v62, v76
	v_add_f32_e32 v76, v63, v76
	v_add_f32_e32 v76, 0, v76
	v_cvt_pk_bf16_f32 v130, v60, v61
	v_cvt_pk_bf16_f32 v131, v62, v63
	s_mov_b64 s[20:21], 0x6000
	v_lshl_add_u64 v[60:61], v[180:181], 0, s[20:21]
	s_add_i32 s20, s43, s39
	s_mov_b32 s21, m0
	s_mov_b32 m0, s20
	s_nop 0
	global_load_lds_dwordx4 v[60:61], off
	s_mov_b32 m0, s21
	v_lshl_add_u64 v[60:61], v[182:183], 0, s[48:49]
	s_add_i32 s20, s42, s35
	s_mov_b32 s21, m0
	s_mov_b32 m0, s20
	s_nop 0
	global_load_lds_dwordx4 v[60:61], off
	s_mov_b32 m0, s21
	v_add_f32_e32 v184, v184, v76
	s_waitcnt lgkmcnt(14)
	v_mfma_f32_32x32x16_bf16 v[0:15], v[148:151], v[176:179], v[0:15]
	v_exp_f32_e32 v96, v96
	v_exp_f32_e32 v97, v97
	v_exp_f32_e32 v98, v98
	v_exp_f32_e32 v99, v99
	s_waitcnt lgkmcnt(12)
	v_mfma_f32_32x32x16_bf16 v[16:31], v[148:151], v[172:175], v[16:31]
	v_exp_f32_e32 v100, v100
	v_exp_f32_e32 v101, v101
	v_exp_f32_e32 v102, v102
	v_exp_f32_e32 v103, v103
	v_add_u32_e32 v76, s42, v225
	ds_read_b128 v[60:63], v76
	ds_read_b128 v[172:175], v76 offset:512
	s_waitcnt lgkmcnt(12)
	v_mfma_f32_32x32x16_bf16 v[0:15], v[144:147], v[64:67], v[0:15]
	v_exp_f32_e32 v104, v104
	v_exp_f32_e32 v105, v105
	v_exp_f32_e32 v106, v106
	v_exp_f32_e32 v107, v107
	ds_read_b128 v[176:179], v76 offset:2048
	ds_read_b128 v[168:171], v76 offset:2560
	s_waitcnt lgkmcnt(12)
	v_mfma_f32_32x32x16_bf16 v[16:31], v[144:147], v[68:71], v[16:31]
	v_exp_f32_e32 v108, v108
	v_exp_f32_e32 v109, v109
	v_exp_f32_e32 v110, v110
	v_exp_f32_e32 v111, v111
	ds_read_b128 v[164:167], v76 offset:4096
	ds_read_b128 v[160:163], v76 offset:4608
	s_waitcnt lgkmcnt(12)
	v_mfma_f32_32x32x16_bf16 v[0:15], v[136:139], v[72:75], v[0:15]
	v_exp_f32_e32 v80, v80
	v_exp_f32_e32 v81, v81
	v_exp_f32_e32 v82, v82
	v_exp_f32_e32 v83, v83
	ds_read_b128 v[124:127], v76 offset:6144
	ds_read_b128 v[120:123], v76 offset:6656
	s_waitcnt lgkmcnt(12)
	v_mfma_f32_32x32x16_bf16 v[16:31], v[136:139], v[48:51], v[16:31]
	v_exp_f32_e32 v84, v84
	v_exp_f32_e32 v85, v85
	v_exp_f32_e32 v86, v86
	v_exp_f32_e32 v87, v87
	s_waitcnt lgkmcnt(10)
	v_mfma_f32_32x32x16_bf16 v[0:15], v[128:131], v[52:55], v[0:15]
	v_exp_f32_e32 v88, v88
	v_exp_f32_e32 v89, v89
	v_exp_f32_e32 v90, v90
	v_exp_f32_e32 v91, v91
	s_waitcnt lgkmcnt(8)
	v_mfma_f32_32x32x16_bf16 v[16:31], v[128:131], v[56:59], v[16:31]
	v_exp_f32_e32 v92, v92
	v_exp_f32_e32 v93, v93
	v_exp_f32_e32 v94, v94
	v_exp_f32_e32 v95, v95
	s_waitcnt vmcnt(2) lgkmcnt(0)
	s_barrier
	s_add_i32 s20, s42, 0x2000
	s_cmpk_lg_i32 s42, 0x4000
	s_cselect_b32 s44, s20, 0
	v_add_u32_e32 v185, s43, v224
	ds_read_b64_tr_b16 v[116:117], v185 offset:24576
	ds_read_b64_tr_b16 v[118:119], v185 offset:25088
	s_waitcnt lgkmcnt(9)
	v_mfma_f32_32x32x16_bf16 v[64:79], v[60:63], v[156:159], v[32:47]
	v_add_f32_e32 v48, v96, v97
	v_add_f32_e32 v48, v98, v48
	v_add_f32_e32 v48, v99, v48
	v_add_f32_e32 v48, v100, v48
	v_add_f32_e32 v48, v101, v48
	v_cvt_pk_bf16_f32 v148, v96, v97
	v_cvt_pk_bf16_f32 v149, v98, v99
	ds_read_b64_tr_b16 v[112:113], v185 offset:28672
	ds_read_b64_tr_b16 v[114:115], v185 offset:29184
	v_add_f32_e32 v48, v102, v48
	v_add_f32_e32 v48, v103, v48
	v_add_f32_e32 v48, v104, v48
	v_add_f32_e32 v128, v105, v48
	s_waitcnt lgkmcnt(10)
	v_mfma_f32_32x32x16_bf16 v[48:63], v[172:175], v[156:159], v[32:47]
	v_cvt_pk_bf16_f32 v150, v100, v101
	v_cvt_pk_bf16_f32 v151, v102, v103
	ds_read_b64_tr_b16 v[96:97], v185 offset:25600
	ds_read_b64_tr_b16 v[98:99], v185 offset:26112
	s_waitcnt lgkmcnt(11)
	v_mfma_f32_32x32x16_bf16 v[64:79], v[176:179], v[152:155], v[64:79]
	v_add_f32_e32 v100, v106, v128
	v_add_f32_e32 v100, v107, v100
	v_add_f32_e32 v100, v108, v100
	v_add_f32_e32 v128, v109, v100
	v_cvt_pk_bf16_f32 v144, v104, v105
	v_cvt_pk_bf16_f32 v145, v106, v107
	ds_read_b64_tr_b16 v[100:101], v185 offset:29696
	ds_read_b64_tr_b16 v[102:103], v185 offset:30208
	s_waitcnt lgkmcnt(12)
	v_mfma_f32_32x32x16_bf16 v[48:63], v[168:171], v[152:155], v[48:63]
	v_add_f32_e32 v104, v110, v128
	v_add_f32_e32 v104, v111, v104
	v_add_f32_e32 v104, v80, v104
	v_add_f32_e32 v128, v81, v104
	v_cvt_pk_bf16_f32 v146, v108, v109
	v_cvt_pk_bf16_f32 v147, v110, v111
	ds_read_b64_tr_b16 v[104:105], v185 offset:26624
	ds_read_b64_tr_b16 v[106:107], v185 offset:27136
	s_waitcnt lgkmcnt(13)
	v_mfma_f32_32x32x16_bf16 v[64:79], v[164:167], v[140:143], v[64:79]
	v_add_f32_e32 v108, v82, v128
	v_add_f32_e32 v108, v83, v108
	v_add_f32_e32 v108, v84, v108
	v_add_f32_e32 v128, v85, v108
	v_cvt_pk_bf16_f32 v136, v80, v81
	v_cvt_pk_bf16_f32 v137, v82, v83
	ds_read_b64_tr_b16 v[108:109], v185 offset:30720
	ds_read_b64_tr_b16 v[110:111], v185 offset:31232
	s_waitcnt lgkmcnt(14)
	v_mfma_f32_32x32x16_bf16 v[48:63], v[160:163], v[140:143], v[48:63]
	v_add_f32_e32 v80, v86, v128
	v_add_f32_e32 v80, v87, v80
	v_add_f32_e32 v80, v88, v80
	v_add_f32_e32 v80, v89, v80
	v_cvt_pk_bf16_f32 v138, v84, v85
	v_cvt_pk_bf16_f32 v139, v86, v87
	ds_read_b64_tr_b16 v[84:85], v185 offset:27648
	ds_read_b64_tr_b16 v[86:87], v185 offset:28160
	s_waitcnt lgkmcnt(14)
	v_mfma_f32_32x32x16_bf16 v[64:79], v[124:127], v[132:135], v[64:79]
	v_add_f32_e32 v80, v90, v80
	v_add_f32_e32 v80, v91, v80
	v_add_f32_e32 v80, v92, v80
	v_add_f32_e32 v80, v93, v80
	v_cvt_pk_bf16_f32 v128, v88, v89
	v_cvt_pk_bf16_f32 v129, v90, v91
	ds_read_b64_tr_b16 v[88:89], v185 offset:31744
	ds_read_b64_tr_b16 v[90:91], v185 offset:32256
	v_mfma_f32_32x32x16_bf16 v[48:63], v[120:123], v[132:135], v[48:63]
	v_add_f32_e32 v80, v94, v80
	v_add_f32_e32 v80, v95, v80
	v_add_f32_e32 v82, 0, v80
	v_cvt_pk_bf16_f32 v130, v92, v93
	v_cvt_pk_bf16_f32 v131, v94, v95
	v_lshl_add_u64 v[80:81], v[180:181], 0, s[88:89]
	s_add_i32 s20, s42, s39
	s_mov_b32 s21, m0
	s_mov_b32 m0, s20
	s_nop 0
	global_load_lds_dwordx4 v[80:81], off
	s_mov_b32 m0, s21
	s_mov_b64 s[20:21], 0x4000
	v_lshl_add_u64 v[182:183], v[182:183], 0, s[20:21]
	s_add_i32 s20, s44, s35
	s_mov_b32 s21, m0
	s_mov_b32 m0, s20
	s_nop 0
	global_load_lds_dwordx4 v[182:183], off
	s_mov_b32 m0, s21
	v_add_f32_e32 v184, v184, v82
	s_waitcnt lgkmcnt(14)
	v_mfma_f32_32x32x16_bf16 v[0:15], v[148:151], v[116:119], v[0:15]
	v_exp_f32_e32 v64, v64
	v_exp_f32_e32 v65, v65
	v_exp_f32_e32 v66, v66
	v_exp_f32_e32 v67, v67
	s_waitcnt lgkmcnt(12)
	v_mfma_f32_32x32x16_bf16 v[16:31], v[148:151], v[112:115], v[16:31]
	v_exp_f32_e32 v68, v68
	v_exp_f32_e32 v69, v69
	v_exp_f32_e32 v70, v70
	v_exp_f32_e32 v71, v71
	v_add_u32_e32 v92, s44, v225
	ds_read_b128 v[80:83], v92
	ds_read_b128 v[164:167], v92 offset:512
	s_waitcnt lgkmcnt(12)
	v_mfma_f32_32x32x16_bf16 v[0:15], v[144:147], v[96:99], v[0:15]
	v_exp_f32_e32 v72, v72
	v_exp_f32_e32 v73, v73
	v_exp_f32_e32 v74, v74
	v_exp_f32_e32 v75, v75
	ds_read_b128 v[168:171], v92 offset:2048
	ds_read_b128 v[160:163], v92 offset:2560
	s_waitcnt lgkmcnt(12)
	v_mfma_f32_32x32x16_bf16 v[16:31], v[144:147], v[100:103], v[16:31]
	v_exp_f32_e32 v76, v76
	v_exp_f32_e32 v77, v77
	v_exp_f32_e32 v78, v78
	v_exp_f32_e32 v79, v79
	ds_read_b128 v[124:127], v92 offset:4096
	ds_read_b128 v[120:123], v92 offset:4608
	s_waitcnt lgkmcnt(12)
	v_mfma_f32_32x32x16_bf16 v[0:15], v[136:139], v[104:107], v[0:15]
	v_exp_f32_e32 v48, v48
	v_exp_f32_e32 v49, v49
	v_exp_f32_e32 v50, v50
	v_exp_f32_e32 v51, v51
	ds_read_b128 v[116:119], v92 offset:6144
	ds_read_b128 v[112:115], v92 offset:6656
	s_waitcnt lgkmcnt(12)
	v_mfma_f32_32x32x16_bf16 v[16:31], v[136:139], v[108:111], v[16:31]
	v_exp_f32_e32 v52, v52
	v_exp_f32_e32 v53, v53
	v_exp_f32_e32 v54, v54
	v_exp_f32_e32 v55, v55
	s_waitcnt lgkmcnt(10)
	v_mfma_f32_32x32x16_bf16 v[0:15], v[128:131], v[84:87], v[0:15]
	v_exp_f32_e32 v56, v56
	v_exp_f32_e32 v57, v57
	v_exp_f32_e32 v58, v58
	v_exp_f32_e32 v59, v59
	s_waitcnt lgkmcnt(8)
	v_mfma_f32_32x32x16_bf16 v[16:31], v[128:131], v[88:91], v[16:31]
	v_exp_f32_e32 v60, v60
	v_exp_f32_e32 v61, v61
	v_exp_f32_e32 v62, v62
	v_exp_f32_e32 v63, v63
	s_waitcnt vmcnt(2) lgkmcnt(0)
	s_barrier
	s_add_i32 s20, s44, 0x2000
	s_cmpk_lg_i32 s44, 0x4000
	s_cselect_b32 s21, s20, 0
	s_add_i32 s41, s41, 2
	s_mov_b64 s[30:31], 0x4000
	s_cmp_lt_u32 s41, 57
	v_lshl_add_u64 v[180:181], v[180:181], 0, s[30:31]
	s_cbranch_scc0 .LBB0_401
	s_mov_b32 s20, s42
	s_mov_b32 s43, s44
	s_mov_b32 s42, s21
	s_branch .Lattn_fast_top
